# v44 with the attention s_setprio 1 moved up to cover each MFMA block's initial LDS reads
# baseline (speedup 1.0000x reference)
; __device__ __forceinline__ unsigned cvt_pk_bf16(float lo, float hi) { unsigned r; asm volatile("v_cvt_pk_bf16_f32 %0, %1, %2" : "=v"(r) : "v"(lo), "v"(hi)); return r; }
; #define LAS __attribute__((address_space(3)))
; template <bool MLA, bool grpB>
; __device__ __forceinline__ void attn_unit_g(LAS unsigned char* lds, const AttnPtrs& P, int b, int h, int qblk) {
;     ...
;         float ps = 0.f;
; #pragma unroll
;         for (int blk = 0; blk < 2; ++blk)
; #pragma unroll
;             for (int r = 0; r < 16; ++r) { const float pv_ = __builtin_amdgcn_exp2f(sc[blk][r] - mref); sc[blk][r] = pv_; ps += pv_; }
;         lrun += ps;
; #pragma unroll
;         for (int blk = 0; blk < 2; ++blk)
; #pragma unroll
;             for (int ks = 0; ks < 2; ++ks) { u32x4 w;
;                 w.x = pg8::cvt_pk_bf16(sc[blk][8 * ks + 0], sc[blk][8 * ks + 1]); w.y = pg8::cvt_pk_bf16(sc[blk][8 * ks + 2], sc[blk][8 * ks + 3]);
;                 w.z = pg8::cvt_pk_bf16(sc[blk][8 * ks + 4], sc[blk][8 * ks + 5]); w.w = pg8::cvt_pk_bf16(sc[blk][8 * ks + 6], sc[blk][8 * ks + 7]);
;                 pb[blk][ks] = __builtin_bit_cast(bf16x8, w); }
;         __builtin_amdgcn_sched_barrier(0);
;     };
;     auto pv = [&](int voff) {
;         const LAS unsigned char* va = lds + varow + voff;
;         bf16x8 a[PFD];
;         auto ld = [&](int i) -> bf16x8 {
;             const int dvb = i & 3, bk = i >> 2, so = ((4 * (bk >> 1) + 2 * hi + (bk & 1)) ^ vswz) * 16;
;             return *(const LAS bf16x8*)(va + 32 * dvb * VROW + so);
;         };
; #pragma unroll
;         for (int i = 0; i < PFD; ++i) a[i] = ld(i);
; #pragma unroll
;         for (int i = 0; i < 16; ++i) {
;             o[i & 3] = __builtin_amdgcn_mfma_f32_32x32x16_bf16(a[i % PFD], pb[i >> 3][(i >> 2) & 1], o[i & 3], 0, 0, 0);
;             if (i + PFD < 16) a[i % PFD] = ld(i + PFD);
;         }
;         __builtin_amdgcn_sched_group_barrier(0x100, PFD, 0);
; #pragma unroll
;         for (int i = 0; i < 16; ++i) { __builtin_amdgcn_sched_group_barrier(0x008, 1, 0); __builtin_amdgcn_sched_group_barrier(0x100, 1, 0); }
;         __builtin_amdgcn_sched_barrier(0);
.LBB0_1151:
	v_sub_f32_e32 v18, v18, v178
	v_exp_f32_e32 v18, v18
	v_sub_f32_e32 v19, v19, v178
	v_exp_f32_e32 v19, v19
	v_sub_f32_e32 v20, v20, v178
	v_exp_f32_e32 v20, v20
	v_sub_f32_e32 v21, v21, v178
	v_exp_f32_e32 v21, v21
	v_sub_f32_e32 v22, v22, v178
	v_add_f32_e32 v179, 0, v18
	v_exp_f32_e32 v22, v22
	v_sub_f32_e32 v23, v23, v178
	v_add_f32_e32 v179, v19, v179
	v_exp_f32_e32 v23, v23
	v_sub_f32_e32 v24, v24, v178
	v_add_f32_e32 v179, v20, v179
	v_exp_f32_e32 v24, v24
	v_sub_f32_e32 v25, v25, v178
	v_add_f32_e32 v179, v21, v179
	v_exp_f32_e32 v25, v25
	v_sub_f32_e32 v26, v26, v178
	v_add_f32_e32 v179, v22, v179
	v_exp_f32_e32 v26, v26
	v_sub_f32_e32 v27, v27, v178
	v_add_f32_e32 v179, v23, v179
	v_exp_f32_e32 v27, v27
	v_sub_f32_e32 v28, v28, v178
	v_add_f32_e32 v179, v24, v179
	v_exp_f32_e32 v28, v28
	v_sub_f32_e32 v29, v29, v178
	v_add_f32_e32 v179, v25, v179
	v_exp_f32_e32 v29, v29
	v_sub_f32_e32 v30, v30, v178
	v_add_f32_e32 v179, v26, v179
	v_exp_f32_e32 v30, v30
	v_sub_f32_e32 v31, v31, v178
	v_add_f32_e32 v179, v27, v179
	v_exp_f32_e32 v31, v31
	v_sub_f32_e32 v32, v32, v178
	v_add_f32_e32 v179, v28, v179
	v_exp_f32_e32 v32, v32
	v_sub_f32_e32 v33, v33, v178
	v_add_f32_e32 v179, v29, v179
	v_exp_f32_e32 v33, v33
	v_sub_f32_e32 v50, v50, v178
	v_add_f32_e32 v179, v30, v179
	v_exp_f32_e32 v50, v50
	v_sub_f32_e32 v51, v51, v178
	v_add_f32_e32 v179, v31, v179
	v_exp_f32_e32 v51, v51
	v_sub_f32_e32 v52, v52, v178
	v_add_f32_e32 v179, v32, v179
	v_exp_f32_e32 v52, v52
	v_sub_f32_e32 v53, v53, v178
	v_add_f32_e32 v179, v33, v179
	v_exp_f32_e32 v53, v53
	v_sub_f32_e32 v54, v54, v178
	v_add_f32_e32 v179, v50, v179
	v_exp_f32_e32 v54, v54
	v_sub_f32_e32 v55, v55, v178
	v_add_f32_e32 v179, v51, v179
	v_exp_f32_e32 v55, v55
	v_sub_f32_e32 v56, v56, v178
	v_add_f32_e32 v179, v52, v179
	v_exp_f32_e32 v56, v56
	v_sub_f32_e32 v57, v57, v178
	v_add_f32_e32 v179, v53, v179
	v_exp_f32_e32 v57, v57
	v_sub_f32_e32 v58, v58, v178
	v_add_f32_e32 v179, v54, v179
	v_exp_f32_e32 v58, v58
	v_sub_f32_e32 v59, v59, v178
	v_add_f32_e32 v179, v55, v179
	v_exp_f32_e32 v59, v59
	v_sub_f32_e32 v60, v60, v178
	v_add_f32_e32 v179, v56, v179
	v_exp_f32_e32 v60, v60
	v_sub_f32_e32 v61, v61, v178
	v_add_f32_e32 v179, v57, v179
	v_exp_f32_e32 v61, v61
	v_sub_f32_e32 v62, v62, v178
	v_add_f32_e32 v179, v58, v179
	v_exp_f32_e32 v62, v62
	v_sub_f32_e32 v63, v63, v178
	v_add_f32_e32 v179, v59, v179
	v_exp_f32_e32 v63, v63
	v_sub_f32_e32 v64, v64, v178
	v_add_f32_e32 v179, v60, v179
	v_exp_f32_e32 v64, v64
	v_sub_f32_e32 v65, v65, v178
	v_add_f32_e32 v179, v61, v179
	v_exp_f32_e32 v65, v65
	v_add_f32_e32 v179, v62, v179
	v_add_f32_e32 v179, v63, v179
	v_add_f32_e32 v179, v64, v179
	v_add_f32_e32 v179, v65, v179
	v_add_f32_e32 v176, v176, v179
	v_cvt_pk_bf16_f32 v180, v18, v19
	v_cvt_pk_bf16_f32 v181, v20, v21
	v_cvt_pk_bf16_f32 v182, v22, v23
	v_cvt_pk_bf16_f32 v183, v24, v25
	v_cvt_pk_bf16_f32 v184, v26, v27
	v_cvt_pk_bf16_f32 v185, v28, v29
	v_cvt_pk_bf16_f32 v186, v30, v31
	v_cvt_pk_bf16_f32 v187, v32, v33
	v_cvt_pk_bf16_f32 v188, v50, v51
	v_cvt_pk_bf16_f32 v189, v52, v53
	v_cvt_pk_bf16_f32 v190, v54, v55
	v_cvt_pk_bf16_f32 v191, v56, v57
	v_cvt_pk_bf16_f32 v192, v58, v59
	v_cvt_pk_bf16_f32 v193, v60, v61
	v_cvt_pk_bf16_f32 v194, v62, v63
	v_cvt_pk_bf16_f32 v195, v64, v65
	v_add_u32_e32 v179, s12, v167
	v_add_u32_e32 v210, v179, v168
	s_setprio 1
	ds_read_b128 v[196:199], v210
	ds_read_b128 v[202:205], v210 offset:4096
	ds_read_b128 v[206:209], v210 offset:8192
	ds_read_b128 v[210:213], v210 offset:12288
	v_add_u32_e32 v222, v179, v169
	ds_read_b128 v[214:217], v222
	ds_read_b128 v[218:221], v222 offset:4096
	s_waitcnt lgkmcnt(5)
	v_mfma_f32_32x32x16_bf16 v[82:97], v[196:199], v[180:183], v[82:97]
	ds_read_b128 v[196:199], v222 offset:8192
	s_waitcnt lgkmcnt(5)
	v_mfma_f32_32x32x16_bf16 v[66:81], v[202:205], v[180:183], v[66:81]
	ds_read_b128 v[202:205], v222 offset:12288
	v_add_u32_e32 v222, v179, v175
	v_add_u32_e32 v179, v179, v177
	s_waitcnt lgkmcnt(5)
	v_mfma_f32_32x32x16_bf16 v[34:49], v[206:209], v[180:183], v[34:49]
	ds_read_b128 v[206:209], v222
	s_waitcnt lgkmcnt(5)
	v_mfma_f32_32x32x16_bf16 v[2:17], v[210:213], v[180:183], v[2:17]
	ds_read_b128 v[180:183], v222 offset:4096
	s_waitcnt lgkmcnt(5)
	v_mfma_f32_32x32x16_bf16 v[82:97], v[214:217], v[184:187], v[82:97]
	ds_read_b128 v[210:213], v222 offset:8192
	s_waitcnt lgkmcnt(5)
	v_mfma_f32_32x32x16_bf16 v[66:81], v[218:221], v[184:187], v[66:81]
	ds_read_b128 v[214:217], v222 offset:12288
	s_waitcnt lgkmcnt(5)
	v_mfma_f32_32x32x16_bf16 v[34:49], v[196:199], v[184:187], v[34:49]
	ds_read_b128 v[196:199], v179
	s_waitcnt lgkmcnt(5)
	v_mfma_f32_32x32x16_bf16 v[2:17], v[202:205], v[184:187], v[2:17]
	ds_read_b128 v[184:187], v179 offset:4096
	s_waitcnt lgkmcnt(5)
	v_mfma_f32_32x32x16_bf16 v[82:97], v[206:209], v[188:191], v[82:97]
	ds_read_b128 v[202:205], v179 offset:8192
	s_waitcnt lgkmcnt(5)
	v_mfma_f32_32x32x16_bf16 v[66:81], v[180:183], v[188:191], v[66:81]
	ds_read_b128 v[180:183], v179 offset:12288
	s_waitcnt lgkmcnt(5)
	v_mfma_f32_32x32x16_bf16 v[34:49], v[210:213], v[188:191], v[34:49]
	s_waitcnt lgkmcnt(4)
	v_mfma_f32_32x32x16_bf16 v[2:17], v[214:217], v[188:191], v[2:17]
	s_waitcnt lgkmcnt(3)
	v_mfma_f32_32x32x16_bf16 v[82:97], v[196:199], v[192:195], v[82:97]
	s_waitcnt lgkmcnt(2)
	v_mfma_f32_32x32x16_bf16 v[66:81], v[184:187], v[192:195], v[66:81]
	s_waitcnt lgkmcnt(1)
	v_mfma_f32_32x32x16_bf16 v[34:49], v[202:205], v[192:195], v[34:49]
	s_waitcnt lgkmcnt(0)
	v_mfma_f32_32x32x16_bf16 v[2:17], v[180:183], v[192:195], v[2:17]
	s_setprio 0
; #define LAS __attribute__((address_space(3)))
; template <bool MLA, bool grpB>
; __device__ __forceinline__ void attn_unit_g(LAS unsigned char* lds, const AttnPtrs& P, int b, int h, int qblk) {
;     ...
;     auto qk = [&](int koff) {
;         if (MLA) {
;         } else {
; #pragma unroll
;             for (int blk = 0; blk < 2; ++blk)
; #pragma unroll
;                 for (int g = 0; g < 4; ++g) { const f32x4 c4 = *(const LAS f32x4*)(lds + koff + KTILE + (32 * blk + 16 * hi + 4 * g) * 4);
; #pragma unroll
;                     for (int e = 0; e < 4; ++e) sc[blk][4 * g + e] = c4[e]; }
;         }
;         const LAS unsigned char* ka = lds + koff + karow;
;         bf16x8 a[PFD];
;         auto ld = [&](int i) -> bf16x8 {
;             const int d0 = i >> 1, blk = i & 1, seg = 2 * d0;
;             int so;
;             if (MLA) so = (((seg + hi) & 24) | (((seg + hi) ^ kswz) & 7)) * 16; else so = ((seg + hi) ^ kswz) * 16;
;             return *(const LAS bf16x8*)(ka + blk * 32 * KROW + so);
;         };
; #pragma unroll
;         for (int i = 0; i < PFD; ++i) a[i] = ld(i);
; #pragma unroll
;         for (int i = 0; i < 2 * ND0; ++i) {
;             const f32x16 zc = {0.f, 0.f, 0.f, 0.f, 0.f, 0.f, 0.f, 0.f, 0.f, 0.f, 0.f, 0.f, 0.f, 0.f, 0.f, 0.f};
;             sc[i & 1] = __builtin_amdgcn_mfma_f32_32x32x16_bf16(a[i % PFD], qf[i >> 1], (MLA && i < 2) ? zc : sc[i & 1], 0, 0, 0);
;             if (i + PFD < 2 * ND0) a[i % PFD] = ld(i + PFD);
;         }
;         __builtin_amdgcn_sched_group_barrier(0x100, PFD, 0);
; #pragma unroll
;         for (int i = 0; i < 2 * ND0; ++i) { __builtin_amdgcn_sched_group_barrier(0x008, 1, 0); __builtin_amdgcn_sched_group_barrier(0x100, 1, 0); }
;         __builtin_amdgcn_sched_barrier(0);
;     ...
;         else { if (j <= my_last) { sm(j); pv(vcur); } if (j > 0 && j - 1 <= my_last) qk(knext); }
.LBB0_1152:
	s_cmp_eq_u32 s36, -3
	s_cselect_b64 s[26:27], -1, 0
	s_cmp_gt_i32 s16, s13
	s_cselect_b64 s[16:17], -1, 0
	s_or_b64 s[16:17], s[26:27], s[16:17]
	s_and_b64 vcc, exec, s[16:17]
	s_cbranch_vccnz .LBB0_1156
	v_add_u32_e32 v54, s23, v161
	v_add_u32_e32 v179, v54, v162
	s_setprio 1
	ds_read_b128 v[18:21], v179
	ds_read_b128 v[50:53], v179 offset:12288
	v_add_u32_e32 v206, v54, v163
	v_add_u32_e32 v207, v54, v164
	ds_read_b128 v[180:183], v206
	ds_read_b128 v[184:187], v206 offset:12288
	v_add_u32_e32 v208, v54, v165
	ds_read_b128 v[188:191], v207
	ds_read_b128 v[192:195], v207 offset:12288
	s_waitcnt lgkmcnt(5)
	v_mfma_f32_32x32x16_bf16 v[18:33], v[18:21], v[98:101], 0
	ds_read_b128 v[196:199], v208
	s_waitcnt lgkmcnt(5)
	v_mfma_f32_32x32x16_bf16 v[50:65], v[50:53], v[98:101], 0
	ds_read_b128 v[202:205], v208 offset:12288
	s_waitcnt lgkmcnt(5)
	v_mfma_f32_32x32x16_bf16 v[18:33], v[180:183], v[102:105], v[18:33]
	ds_read_b128 v[180:183], v179 offset:128
	s_waitcnt lgkmcnt(5)
	v_mfma_f32_32x32x16_bf16 v[50:65], v[184:187], v[102:105], v[50:65]
	ds_read_b128 v[184:187], v179 offset:12416
	s_waitcnt lgkmcnt(5)
	v_mfma_f32_32x32x16_bf16 v[18:33], v[188:191], v[106:109], v[18:33]
	ds_read_b128 v[188:191], v206 offset:128
	s_waitcnt lgkmcnt(5)
	v_mfma_f32_32x32x16_bf16 v[50:65], v[192:195], v[106:109], v[50:65]
	ds_read_b128 v[192:195], v206 offset:12416
	s_waitcnt lgkmcnt(5)
	v_mfma_f32_32x32x16_bf16 v[18:33], v[196:199], v[110:113], v[18:33]
	ds_read_b128 v[196:199], v207 offset:128
	s_waitcnt lgkmcnt(5)
	v_mfma_f32_32x32x16_bf16 v[50:65], v[202:205], v[110:113], v[50:65]
	ds_read_b128 v[202:205], v207 offset:12416
	s_waitcnt lgkmcnt(5)
	v_mfma_f32_32x32x16_bf16 v[18:33], v[180:183], v[114:117], v[18:33]
	ds_read_b128 v[180:183], v208 offset:128
	s_waitcnt lgkmcnt(5)
	v_mfma_f32_32x32x16_bf16 v[50:65], v[184:187], v[114:117], v[50:65]
	ds_read_b128 v[184:187], v208 offset:12416
	s_waitcnt lgkmcnt(5)
	v_mfma_f32_32x32x16_bf16 v[18:33], v[188:191], v[118:121], v[18:33]
	ds_read_b128 v[188:191], v179 offset:256
	s_waitcnt lgkmcnt(5)
	v_mfma_f32_32x32x16_bf16 v[50:65], v[192:195], v[118:121], v[50:65]
	ds_read_b128 v[192:195], v179 offset:12544
	s_waitcnt lgkmcnt(5)
	v_mfma_f32_32x32x16_bf16 v[18:33], v[196:199], v[122:125], v[18:33]
	ds_read_b128 v[196:199], v206 offset:256
	s_waitcnt lgkmcnt(5)
	v_mfma_f32_32x32x16_bf16 v[50:65], v[202:205], v[122:125], v[50:65]
	ds_read_b128 v[202:205], v206 offset:12544
	s_waitcnt lgkmcnt(5)
	v_mfma_f32_32x32x16_bf16 v[18:33], v[180:183], v[126:129], v[18:33]
	ds_read_b128 v[180:183], v207 offset:256
	s_waitcnt lgkmcnt(5)
	v_mfma_f32_32x32x16_bf16 v[50:65], v[184:187], v[126:129], v[50:65]
	ds_read_b128 v[184:187], v207 offset:12544
	s_waitcnt lgkmcnt(5)
	v_mfma_f32_32x32x16_bf16 v[18:33], v[188:191], v[130:133], v[18:33]
	ds_read_b128 v[188:191], v208 offset:256
	s_waitcnt lgkmcnt(5)
	v_mfma_f32_32x32x16_bf16 v[50:65], v[192:195], v[130:133], v[50:65]
	ds_read_b128 v[192:195], v208 offset:12544
	s_waitcnt lgkmcnt(5)
	v_mfma_f32_32x32x16_bf16 v[18:33], v[196:199], v[134:137], v[18:33]
	s_waitcnt lgkmcnt(4)
	v_mfma_f32_32x32x16_bf16 v[50:65], v[202:205], v[134:137], v[50:65]
	s_waitcnt lgkmcnt(3)
	v_mfma_f32_32x32x16_bf16 v[18:33], v[180:183], v[138:141], v[18:33]
	s_waitcnt lgkmcnt(2)
	v_mfma_f32_32x32x16_bf16 v[50:65], v[184:187], v[138:141], v[50:65]
	s_waitcnt lgkmcnt(1)
	v_mfma_f32_32x32x16_bf16 v[18:33], v[188:191], v[142:145], v[18:33]
	s_waitcnt lgkmcnt(0)
	v_mfma_f32_32x32x16_bf16 v[50:65], v[192:195], v[142:145], v[50:65]
	s_setprio 0
	s_mov_b64 s[16:17], -1
	s_and_b64 vcc, exec, s[14:15]
	s_cbranch_vccnz .LBB0_1157

; #define LAS __attribute__((address_space(3)))
; template <bool MLA, bool grpB>
; __device__ __forceinline__ void attn_unit_g(LAS unsigned char* lds, const AttnPtrs& P, int b, int h, int qblk) {
;     ...
;     auto qk = [&](int koff) {
;         if (MLA) {
;         } else {
; #pragma unroll
;             for (int blk = 0; blk < 2; ++blk)
; #pragma unroll
;                 for (int g = 0; g < 4; ++g) { const f32x4 c4 = *(const LAS f32x4*)(lds + koff + KTILE + (32 * blk + 16 * hi + 4 * g) * 4);
; #pragma unroll
;                     for (int e = 0; e < 4; ++e) sc[blk][4 * g + e] = c4[e]; }
;         }
;         const LAS unsigned char* ka = lds + koff + karow;
;         bf16x8 a[PFD];
;         auto ld = [&](int i) -> bf16x8 {
;             const int d0 = i >> 1, blk = i & 1, seg = 2 * d0;
;             int so;
;             if (MLA) so = (((seg + hi) & 24) | (((seg + hi) ^ kswz) & 7)) * 16; else so = ((seg + hi) ^ kswz) * 16;
;             return *(const LAS bf16x8*)(ka + blk * 32 * KROW + so);
;         };
; #pragma unroll
;         for (int i = 0; i < PFD; ++i) a[i] = ld(i);
; #pragma unroll
;         for (int i = 0; i < 2 * ND0; ++i) {
;             const f32x16 zc = {0.f, 0.f, 0.f, 0.f, 0.f, 0.f, 0.f, 0.f, 0.f, 0.f, 0.f, 0.f, 0.f, 0.f, 0.f, 0.f};
;             sc[i & 1] = __builtin_amdgcn_mfma_f32_32x32x16_bf16(a[i % PFD], qf[i >> 1], (MLA && i < 2) ? zc : sc[i & 1], 0, 0, 0);
;             if (i + PFD < 2 * ND0) a[i % PFD] = ld(i + PFD);
;         }
;         __builtin_amdgcn_sched_group_barrier(0x100, PFD, 0);
; #pragma unroll
;         for (int i = 0; i < 2 * ND0; ++i) { __builtin_amdgcn_sched_group_barrier(0x008, 1, 0); __builtin_amdgcn_sched_group_barrier(0x100, 1, 0); }
;         __builtin_amdgcn_sched_barrier(0);
;     };
;     float mref = -1e30f;
;     auto sm = [&](int j) {
;         if (j >= my_last) {
;             if (MLA) { if (j > my_last) {
; #pragma unroll
;                 for (int r = 0; r < 16; ++r) { sc[0][r] = -2e30f; sc[1][r] = -2e30f; } } }
;             else { const int qpos = q0 + r32;
; #pragma unroll
;                 for (int blk = 0; blk < 2; ++blk)
; #pragma unroll
;                     for (int r = 0; r < 16; ++r) { const int key = 64 * j + 32 * blk + 16 * hi + r; if (key > qpos) sc[blk][r] = -2e30f; } }
;         }
;         float big_ = 3.0e38f; asm volatile("" : "+v"(big_));
.LBB0_1214:
	v_add_u32_e32 v0, s26, v179
	v_add_u32_e32 v14, v0, v183
	s_setprio 1
	ds_read_b128 v[2:5], v14
	ds_read_b128 v[6:9], v14 offset:12288
	v_add_u32_e32 v15, v0, v184
	v_add_u32_e32 v198, v0, v185
	ds_read_b128 v[10:13], v15
	ds_read_b128 v[194:197], v15 offset:12288
	v_add_u32_e32 v0, v0, v186
	ds_read_b128 v[202:205], v198
	ds_read_b128 v[206:209], v198 offset:12288
	s_waitcnt lgkmcnt(5)
	v_mfma_f32_32x32x16_bf16 v[96:111], v[2:5], v[112:115], 0
	ds_read_b128 v[2:5], v0
	s_waitcnt lgkmcnt(5)
	v_mfma_f32_32x32x16_bf16 v[80:95], v[6:9], v[112:115], 0
	ds_read_b128 v[6:9], v0 offset:12288
	s_waitcnt lgkmcnt(5)
	v_mfma_f32_32x32x16_bf16 v[96:111], v[10:13], v[116:119], v[96:111]
	ds_read_b128 v[10:13], v14 offset:128
	s_waitcnt lgkmcnt(5)
	v_mfma_f32_32x32x16_bf16 v[80:95], v[194:197], v[116:119], v[80:95]
	ds_read_b128 v[194:197], v14 offset:12416
	s_waitcnt lgkmcnt(5)
	v_mfma_f32_32x32x16_bf16 v[96:111], v[202:205], v[120:123], v[96:111]
	ds_read_b128 v[202:205], v15 offset:128
	s_waitcnt lgkmcnt(5)
	v_mfma_f32_32x32x16_bf16 v[80:95], v[206:209], v[120:123], v[80:95]
	ds_read_b128 v[206:209], v15 offset:12416
	s_waitcnt lgkmcnt(5)
	v_mfma_f32_32x32x16_bf16 v[96:111], v[2:5], v[124:127], v[96:111]
	ds_read_b128 v[2:5], v198 offset:128
	s_waitcnt lgkmcnt(5)
	v_mfma_f32_32x32x16_bf16 v[80:95], v[6:9], v[124:127], v[80:95]
	ds_read_b128 v[6:9], v198 offset:12416
	s_waitcnt lgkmcnt(5)
	v_mfma_f32_32x32x16_bf16 v[96:111], v[10:13], v[128:131], v[96:111]
	ds_read_b128 v[10:13], v0 offset:128
	s_waitcnt lgkmcnt(5)
	v_mfma_f32_32x32x16_bf16 v[80:95], v[194:197], v[128:131], v[80:95]
	ds_read_b128 v[194:197], v0 offset:12416
	s_waitcnt lgkmcnt(5)
	v_mfma_f32_32x32x16_bf16 v[96:111], v[202:205], v[132:135], v[96:111]
	ds_read_b128 v[202:205], v14 offset:256
	s_waitcnt lgkmcnt(5)
	v_mfma_f32_32x32x16_bf16 v[80:95], v[206:209], v[132:135], v[80:95]
	ds_read_b128 v[206:209], v14 offset:12544
	s_waitcnt lgkmcnt(5)
	v_mfma_f32_32x32x16_bf16 v[96:111], v[2:5], v[136:139], v[96:111]
	ds_read_b128 v[2:5], v15 offset:256
	s_waitcnt lgkmcnt(5)
	v_mfma_f32_32x32x16_bf16 v[80:95], v[6:9], v[136:139], v[80:95]
	ds_read_b128 v[6:9], v15 offset:12544
	s_waitcnt lgkmcnt(5)
	v_mfma_f32_32x32x16_bf16 v[96:111], v[10:13], v[140:143], v[96:111]
	ds_read_b128 v[10:13], v198 offset:256
	s_waitcnt lgkmcnt(5)
	v_mfma_f32_32x32x16_bf16 v[80:95], v[194:197], v[140:143], v[80:95]
	ds_read_b128 v[194:197], v198 offset:12544
	s_waitcnt lgkmcnt(5)
	v_mfma_f32_32x32x16_bf16 v[96:111], v[202:205], v[144:147], v[96:111]
	ds_read_b128 v[202:205], v0 offset:256
	s_waitcnt lgkmcnt(5)
	v_mfma_f32_32x32x16_bf16 v[80:95], v[206:209], v[144:147], v[80:95]
	ds_read_b128 v[206:209], v0 offset:12544
	s_waitcnt lgkmcnt(5)
	v_mfma_f32_32x32x16_bf16 v[96:111], v[2:5], v[148:151], v[96:111]
	s_waitcnt lgkmcnt(4)
	v_mfma_f32_32x32x16_bf16 v[80:95], v[6:9], v[148:151], v[80:95]
	s_waitcnt lgkmcnt(3)
	v_mfma_f32_32x32x16_bf16 v[96:111], v[10:13], v[152:155], v[96:111]
	s_waitcnt lgkmcnt(2)
	v_mfma_f32_32x32x16_bf16 v[80:95], v[194:197], v[152:155], v[80:95]
	s_waitcnt lgkmcnt(1)
	v_mfma_f32_32x32x16_bf16 v[96:111], v[202:205], v[156:159], v[96:111]
	s_waitcnt lgkmcnt(0)
	v_mfma_f32_32x32x16_bf16 v[80:95], v[206:209], v[156:159], v[80:95]
	s_setprio 0
	v_mov_b32_e32 v0, 0x7f61b1e6
	s_nop 9
	v_med3_f32 v2, v96, v97, v0
	v_med3_f32 v6, v100, v101, v0
	v_med3_f32 v3, v98, v99, v0
	v_med3_f32 v2, v2, v6, v0
	v_med3_f32 v6, v102, v103, v0
	v_med3_f32 v4, v80, v81, v0
	v_med3_f32 v3, v3, v6, v0
	v_med3_f32 v6, v84, v85, v0
	v_med3_f32 v5, v82, v83, v0
	v_med3_f32 v4, v4, v6, v0
	v_med3_f32 v6, v86, v87, v0
	v_med3_f32 v5, v5, v6, v0
	v_med3_f32 v6, v104, v105, v0
	v_med3_f32 v2, v2, v6, v0
	v_med3_f32 v6, v106, v107, v0
	v_med3_f32 v3, v3, v6, v0
	v_med3_f32 v6, v88, v89, v0
	v_med3_f32 v4, v4, v6, v0
	v_med3_f32 v6, v90, v91, v0
	v_med3_f32 v5, v5, v6, v0
	v_med3_f32 v6, v108, v109, v0
	v_med3_f32 v2, v2, v6, v0
	v_med3_f32 v6, v110, v111, v0
	v_med3_f32 v3, v3, v6, v0
	v_med3_f32 v6, v92, v93, v0
	v_med3_f32 v4, v4, v6, v0
	v_med3_f32 v6, v94, v95, v0
	v_med3_f32 v5, v5, v6, v0
	v_med3_f32 v2, v2, v3, v0
	v_med3_f32 v3, v4, v5, v0
	v_and_b32_e32 v4, 64, v171
	v_med3_f32 v2, v2, v3, v0
	v_xor_b32_e32 v3, 32, v171
	v_add_u32_e32 v4, 64, v4
	v_cmp_lt_i32_e32 vcc, v3, v4
	s_nop 1
	v_cndmask_b32_e32 v3, v171, v3, vcc
	v_lshlrev_b32_e32 v3, 2, v3
	ds_bpermute_b32 v3, v3, v2
	s_waitcnt lgkmcnt(0)
	v_med3_f32 v0, v2, v3, v0
	v_add_f32_e32 v2, 0x41000000, v193
	v_cmp_gt_f32_e32 vcc, v0, v2
	s_cbranch_vccz .LBB0_1216
	v_max_f32_e32 v0, v0, v0
	v_max_f32_e32 v2, v193, v193
	v_max_f32_e32 v2, v2, v0
	v_sub_f32_e32 v0, v193, v2
	v_exp_f32_e32 v0, v0
	v_mov_b32_e32 v193, v2
	v_mul_f32_e32 v192, v192, v0
	v_pk_mul_f32 v[78:79], v[78:79], v[0:1] op_sel_hi:[1,0]
	v_pk_mul_f32 v[76:77], v[76:77], v[0:1] op_sel_hi:[1,0]
	v_pk_mul_f32 v[74:75], v[74:75], v[0:1] op_sel_hi:[1,0]
	v_pk_mul_f32 v[72:73], v[72:73], v[0:1] op_sel_hi:[1,0]
	v_pk_mul_f32 v[70:71], v[70:71], v[0:1] op_sel_hi:[1,0]
	v_pk_mul_f32 v[68:69], v[68:69], v[0:1] op_sel_hi:[1,0]
	v_pk_mul_f32 v[66:67], v[66:67], v[0:1] op_sel_hi:[1,0]
	v_pk_mul_f32 v[64:65], v[64:65], v[0:1] op_sel_hi:[1,0]
	v_pk_mul_f32 v[62:63], v[62:63], v[0:1] op_sel_hi:[1,0]
	v_pk_mul_f32 v[60:61], v[60:61], v[0:1] op_sel_hi:[1,0]
	v_pk_mul_f32 v[58:59], v[58:59], v[0:1] op_sel_hi:[1,0]
	v_pk_mul_f32 v[56:57], v[56:57], v[0:1] op_sel_hi:[1,0]
	v_pk_mul_f32 v[54:55], v[54:55], v[0:1] op_sel_hi:[1,0]
	v_pk_mul_f32 v[52:53], v[52:53], v[0:1] op_sel_hi:[1,0]
	v_pk_mul_f32 v[50:51], v[50:51], v[0:1] op_sel_hi:[1,0]
	v_pk_mul_f32 v[48:49], v[48:49], v[0:1] op_sel_hi:[1,0]
	v_pk_mul_f32 v[46:47], v[46:47], v[0:1] op_sel_hi:[1,0]
	v_pk_mul_f32 v[44:45], v[44:45], v[0:1] op_sel_hi:[1,0]
	v_pk_mul_f32 v[42:43], v[42:43], v[0:1] op_sel_hi:[1,0]
	v_pk_mul_f32 v[40:41], v[40:41], v[0:1] op_sel_hi:[1,0]
	v_pk_mul_f32 v[38:39], v[38:39], v[0:1] op_sel_hi:[1,0]
	v_pk_mul_f32 v[36:37], v[36:37], v[0:1] op_sel_hi:[1,0]
	v_pk_mul_f32 v[34:35], v[34:35], v[0:1] op_sel_hi:[1,0]
	v_pk_mul_f32 v[32:33], v[32:33], v[0:1] op_sel_hi:[1,0]
	v_pk_mul_f32 v[30:31], v[30:31], v[0:1] op_sel_hi:[1,0]
	v_pk_mul_f32 v[28:29], v[28:29], v[0:1] op_sel_hi:[1,0]
	v_pk_mul_f32 v[26:27], v[26:27], v[0:1] op_sel_hi:[1,0]
	v_pk_mul_f32 v[24:25], v[24:25], v[0:1] op_sel_hi:[1,0]
	v_pk_mul_f32 v[22:23], v[22:23], v[0:1] op_sel_hi:[1,0]
	v_pk_mul_f32 v[20:21], v[20:21], v[0:1] op_sel_hi:[1,0]
	v_pk_mul_f32 v[18:19], v[18:19], v[0:1] op_sel_hi:[1,0]
	v_pk_mul_f32 v[16:17], v[16:17], v[0:1] op_sel_hi:[1,0]
; __device__ __forceinline__ unsigned cvt_pk_bf16(float lo, float hi) { unsigned r; asm volatile("v_cvt_pk_bf16_f32 %0, %1, %2" : "=v"(r) : "v"(lo), "v"(hi)); return r; }
; #define LAS __attribute__((address_space(3)))
; template <bool MLA, bool grpB>
; __device__ __forceinline__ void attn_unit_g(LAS unsigned char* lds, const AttnPtrs& P, int b, int h, int qblk) {
;     ...
;         float ps = 0.f;
; #pragma unroll
;         for (int blk = 0; blk < 2; ++blk)
; #pragma unroll
;             for (int r = 0; r < 16; ++r) { const float pv_ = __builtin_amdgcn_exp2f(sc[blk][r] - mref); sc[blk][r] = pv_; ps += pv_; }
;         lrun += ps;
; #pragma unroll
;         for (int blk = 0; blk < 2; ++blk)
; #pragma unroll
;             for (int ks = 0; ks < 2; ++ks) { u32x4 w;
;                 w.x = pg8::cvt_pk_bf16(sc[blk][8 * ks + 0], sc[blk][8 * ks + 1]); w.y = pg8::cvt_pk_bf16(sc[blk][8 * ks + 2], sc[blk][8 * ks + 3]);
;                 w.z = pg8::cvt_pk_bf16(sc[blk][8 * ks + 4], sc[blk][8 * ks + 5]); w.w = pg8::cvt_pk_bf16(sc[blk][8 * ks + 6], sc[blk][8 * ks + 7]);
;                 pb[blk][ks] = __builtin_bit_cast(bf16x8, w); }
;         __builtin_amdgcn_sched_barrier(0);
;     };
;     auto pv = [&](int voff) {
;         const LAS unsigned char* va = lds + varow + voff;
;         bf16x8 a[PFD];
;         auto ld = [&](int i) -> bf16x8 {
;             const int dvb = i & 3, bk = i >> 2, so = ((4 * (bk >> 1) + 2 * hi + (bk & 1)) ^ vswz) * 16;
;             return *(const LAS bf16x8*)(va + 32 * dvb * VROW + so);
;         };
; #pragma unroll
;         for (int i = 0; i < PFD; ++i) a[i] = ld(i);
; #pragma unroll
;         for (int i = 0; i < 16; ++i) {
;             o[i & 3] = __builtin_amdgcn_mfma_f32_32x32x16_bf16(a[i % PFD], pb[i >> 3][(i >> 2) & 1], o[i & 3], 0, 0, 0);
;             if (i + PFD < 16) a[i % PFD] = ld(i + PFD);
;         }
;         __builtin_amdgcn_sched_group_barrier(0x100, PFD, 0);
; #pragma unroll
;         for (int i = 0; i < 16; ++i) { __builtin_amdgcn_sched_group_barrier(0x008, 1, 0); __builtin_amdgcn_sched_group_barrier(0x100, 1, 0); }
;         __builtin_amdgcn_sched_barrier(0);
.LBB0_1216:
	v_sub_f32_e32 v0, v96, v193
	v_exp_f32_e32 v0, v0
	v_sub_f32_e32 v2, v97, v193
	v_exp_f32_e32 v2, v2
	v_sub_f32_e32 v3, v98, v193
	v_exp_f32_e32 v3, v3
	v_sub_f32_e32 v4, v99, v193
	v_exp_f32_e32 v4, v4
	v_sub_f32_e32 v6, v100, v193
	v_add_f32_e32 v5, 0, v0
	v_exp_f32_e32 v6, v6
	v_sub_f32_e32 v7, v101, v193
	v_add_f32_e32 v5, v2, v5
	v_exp_f32_e32 v7, v7
	v_sub_f32_e32 v8, v102, v193
	v_add_f32_e32 v5, v3, v5
	v_exp_f32_e32 v8, v8
	v_sub_f32_e32 v9, v103, v193
	v_add_f32_e32 v5, v4, v5
	v_exp_f32_e32 v9, v9
	v_sub_f32_e32 v10, v104, v193
	v_add_f32_e32 v5, v6, v5
	v_exp_f32_e32 v10, v10
	v_sub_f32_e32 v11, v105, v193
	v_add_f32_e32 v5, v7, v5
	v_exp_f32_e32 v11, v11
	v_sub_f32_e32 v12, v106, v193
	v_add_f32_e32 v5, v8, v5
	v_exp_f32_e32 v12, v12
	v_sub_f32_e32 v13, v107, v193
	v_add_f32_e32 v5, v9, v5
	v_exp_f32_e32 v13, v13
	v_sub_f32_e32 v14, v108, v193
	v_add_f32_e32 v5, v10, v5
	v_exp_f32_e32 v14, v14
	v_sub_f32_e32 v15, v109, v193
	v_add_f32_e32 v5, v11, v5
	v_exp_f32_e32 v15, v15
	v_sub_f32_e32 v96, v110, v193
	v_add_f32_e32 v5, v12, v5
	v_exp_f32_e32 v96, v96
	v_sub_f32_e32 v97, v111, v193
	v_add_f32_e32 v5, v13, v5
	v_exp_f32_e32 v97, v97
	v_sub_f32_e32 v80, v80, v193
	v_add_f32_e32 v5, v14, v5
	v_exp_f32_e32 v80, v80
	v_sub_f32_e32 v81, v81, v193
	v_add_f32_e32 v5, v15, v5
	v_exp_f32_e32 v81, v81
	v_sub_f32_e32 v82, v82, v193
	v_add_f32_e32 v5, v96, v5
	v_exp_f32_e32 v82, v82
	v_sub_f32_e32 v83, v83, v193
	v_add_f32_e32 v5, v97, v5
	v_exp_f32_e32 v83, v83
	v_sub_f32_e32 v84, v84, v193
	v_add_f32_e32 v5, v80, v5
	v_exp_f32_e32 v84, v84
	v_sub_f32_e32 v85, v85, v193
	v_add_f32_e32 v5, v81, v5
	v_exp_f32_e32 v85, v85
	v_sub_f32_e32 v86, v86, v193
	v_add_f32_e32 v5, v82, v5
	v_exp_f32_e32 v86, v86
	v_sub_f32_e32 v87, v87, v193
	v_add_f32_e32 v5, v83, v5
	v_exp_f32_e32 v87, v87
	v_sub_f32_e32 v88, v88, v193
	v_add_f32_e32 v5, v84, v5
	v_exp_f32_e32 v88, v88
	v_sub_f32_e32 v89, v89, v193
	v_add_f32_e32 v5, v85, v5
	v_exp_f32_e32 v89, v89
	v_sub_f32_e32 v90, v90, v193
	v_add_f32_e32 v5, v86, v5
	v_exp_f32_e32 v90, v90
	v_sub_f32_e32 v91, v91, v193
	v_add_f32_e32 v5, v87, v5
	v_exp_f32_e32 v91, v91
	v_sub_f32_e32 v92, v92, v193
	v_add_f32_e32 v5, v88, v5
	v_exp_f32_e32 v92, v92
	v_sub_f32_e32 v93, v93, v193
	v_add_f32_e32 v5, v89, v5
	v_exp_f32_e32 v93, v93
	v_sub_f32_e32 v94, v94, v193
	v_add_f32_e32 v5, v90, v5
	v_exp_f32_e32 v94, v94
	v_sub_f32_e32 v95, v95, v193
	v_add_f32_e32 v5, v91, v5
	v_exp_f32_e32 v95, v95
	v_add_f32_e32 v5, v92, v5
	v_add_f32_e32 v5, v93, v5
	v_add_f32_e32 v5, v94, v5
	v_add_f32_e32 v5, v95, v5
	v_add_f32_e32 v192, v192, v5
	v_cvt_pk_bf16_f32 v2, v0, v2
	v_cvt_pk_bf16_f32 v3, v3, v4
	v_cvt_pk_bf16_f32 v4, v6, v7
	v_cvt_pk_bf16_f32 v5, v8, v9
	v_cvt_pk_bf16_f32 v6, v10, v11
	v_cvt_pk_bf16_f32 v7, v12, v13
	v_cvt_pk_bf16_f32 v8, v14, v15
	v_cvt_pk_bf16_f32 v9, v96, v97
	v_cvt_pk_bf16_f32 v10, v80, v81
	v_cvt_pk_bf16_f32 v11, v82, v83
	v_cvt_pk_bf16_f32 v12, v84, v85
	v_cvt_pk_bf16_f32 v13, v86, v87
	v_cvt_pk_bf16_f32 v80, v88, v89
	v_cvt_pk_bf16_f32 v81, v90, v91
	v_cvt_pk_bf16_f32 v82, v92, v93
	v_cvt_pk_bf16_f32 v83, v94, v95
	v_add_u32_e32 v0, s21, v187
	v_add_u32_e32 v14, v0, v188
	s_setprio 1
	ds_read_b128 v[84:87], v14
	ds_read_b128 v[88:91], v14 offset:4096
	ds_read_b128 v[92:95], v14 offset:8192
	ds_read_b128 v[96:99], v14 offset:12288
	v_add_u32_e32 v15, v0, v189
	ds_read_b128 v[100:103], v15
	ds_read_b128 v[104:107], v15 offset:4096
	v_add_u32_e32 v14, v0, v190
	v_add_u32_e32 v0, v0, v191
	s_waitcnt lgkmcnt(5)
	v_mfma_f32_32x32x16_bf16 v[64:79], v[84:87], v[2:5], v[64:79]
	ds_read_b128 v[84:87], v15 offset:8192
	s_waitcnt lgkmcnt(5)
	v_mfma_f32_32x32x16_bf16 v[48:63], v[88:91], v[2:5], v[48:63]
	ds_read_b128 v[88:91], v15 offset:12288
	s_waitcnt lgkmcnt(5)
	v_mfma_f32_32x32x16_bf16 v[32:47], v[92:95], v[2:5], v[32:47]
	ds_read_b128 v[92:95], v14
	s_waitcnt lgkmcnt(5)
	v_mfma_f32_32x32x16_bf16 v[16:31], v[96:99], v[2:5], v[16:31]
	ds_read_b128 v[2:5], v14 offset:4096
	s_waitcnt lgkmcnt(5)
	v_mfma_f32_32x32x16_bf16 v[64:79], v[100:103], v[6:9], v[64:79]
	ds_read_b128 v[96:99], v14 offset:8192
	s_waitcnt lgkmcnt(5)
	v_mfma_f32_32x32x16_bf16 v[48:63], v[104:107], v[6:9], v[48:63]
	ds_read_b128 v[100:103], v14 offset:12288
	s_waitcnt lgkmcnt(5)
	v_mfma_f32_32x32x16_bf16 v[32:47], v[84:87], v[6:9], v[32:47]
	ds_read_b128 v[84:87], v0
	s_waitcnt lgkmcnt(5)
	v_mfma_f32_32x32x16_bf16 v[16:31], v[88:91], v[6:9], v[16:31]
	ds_read_b128 v[6:9], v0 offset:4096
	s_waitcnt lgkmcnt(5)
	v_mfma_f32_32x32x16_bf16 v[64:79], v[92:95], v[10:13], v[64:79]
	ds_read_b128 v[88:91], v0 offset:8192
	s_waitcnt lgkmcnt(5)
	v_mfma_f32_32x32x16_bf16 v[48:63], v[2:5], v[10:13], v[48:63]
	ds_read_b128 v[2:5], v0 offset:12288
	s_waitcnt lgkmcnt(5)
	v_mfma_f32_32x32x16_bf16 v[32:47], v[96:99], v[10:13], v[32:47]
	s_waitcnt lgkmcnt(4)
	v_mfma_f32_32x32x16_bf16 v[16:31], v[100:103], v[10:13], v[16:31]
	s_waitcnt lgkmcnt(3)
	v_mfma_f32_32x32x16_bf16 v[64:79], v[84:87], v[80:83], v[64:79]
	s_waitcnt lgkmcnt(2)
	v_mfma_f32_32x32x16_bf16 v[48:63], v[6:9], v[80:83], v[48:63]
	s_waitcnt lgkmcnt(1)
	v_mfma_f32_32x32x16_bf16 v[32:47], v[88:91], v[80:83], v[32:47]
	s_waitcnt lgkmcnt(0)
	v_mfma_f32_32x32x16_bf16 v[16:31], v[2:5], v[80:83], v[16:31]
	s_setprio 0
	s_mov_b64 s[16:17], -1
	s_and_b64 vcc, exec, s[14:15]
	s_cbranch_vccnz .LBB0_1208

; __device__ __forceinline__ unsigned cvt_pk_bf16(float lo, float hi) { unsigned r; asm volatile("v_cvt_pk_bf16_f32 %0, %1, %2" : "=v"(r) : "v"(lo), "v"(hi)); return r; }
; #define LAS __attribute__((address_space(3)))
; template <bool MLA, bool grpB>
; __device__ __forceinline__ void attn_unit_g(LAS unsigned char* lds, const AttnPtrs& P, int b, int h, int qblk) {
;     ...
;         float ps = 0.f;
; #pragma unroll
;         for (int blk = 0; blk < 2; ++blk)
; #pragma unroll
;             for (int r = 0; r < 16; ++r) { const float pv_ = __builtin_amdgcn_exp2f(sc[blk][r] - mref); sc[blk][r] = pv_; ps += pv_; }
;         lrun += ps;
; #pragma unroll
;         for (int blk = 0; blk < 2; ++blk)
; #pragma unroll
;             for (int ks = 0; ks < 2; ++ks) { u32x4 w;
;                 w.x = pg8::cvt_pk_bf16(sc[blk][8 * ks + 0], sc[blk][8 * ks + 1]); w.y = pg8::cvt_pk_bf16(sc[blk][8 * ks + 2], sc[blk][8 * ks + 3]);
;                 w.z = pg8::cvt_pk_bf16(sc[blk][8 * ks + 4], sc[blk][8 * ks + 5]); w.w = pg8::cvt_pk_bf16(sc[blk][8 * ks + 6], sc[blk][8 * ks + 7]);
;                 pb[blk][ks] = __builtin_bit_cast(bf16x8, w); }
;         __builtin_amdgcn_sched_barrier(0);
;     };
;     auto pv = [&](int voff) {
;         const LAS unsigned char* va = lds + varow + voff;
;         bf16x8 a[PFD];
;         auto ld = [&](int i) -> bf16x8 {
;             const int dvb = i & 3, bk = i >> 2, so = ((4 * (bk >> 1) + 2 * hi + (bk & 1)) ^ vswz) * 16;
;             return *(const LAS bf16x8*)(va + 32 * dvb * VROW + so);
;         };
; #pragma unroll
;         for (int i = 0; i < PFD; ++i) a[i] = ld(i);
; #pragma unroll
;         for (int i = 0; i < 16; ++i) {
;             o[i & 3] = __builtin_amdgcn_mfma_f32_32x32x16_bf16(a[i % PFD], pb[i >> 3][(i >> 2) & 1], o[i & 3], 0, 0, 0);
;             if (i + PFD < 16) a[i % PFD] = ld(i + PFD);
;         }
;         __builtin_amdgcn_sched_group_barrier(0x100, PFD, 0);
; #pragma unroll
;         for (int i = 0; i < 16; ++i) { __builtin_amdgcn_sched_group_barrier(0x008, 1, 0); __builtin_amdgcn_sched_group_barrier(0x100, 1, 0); }
;         __builtin_amdgcn_sched_barrier(0);
.LBB0_1268:
	v_sub_f32_e32 v0, v16, v181
	v_exp_f32_e32 v16, v0
	v_sub_f32_e32 v0, v17, v181
	v_exp_f32_e32 v17, v0
	v_sub_f32_e32 v0, v18, v181
	v_exp_f32_e32 v18, v0
	v_sub_f32_e32 v0, v19, v181
	v_exp_f32_e32 v19, v0
	v_sub_f32_e32 v2, v20, v181
	v_add_f32_e32 v0, 0, v16
	v_exp_f32_e32 v20, v2
	v_sub_f32_e32 v2, v21, v181
	v_add_f32_e32 v0, v17, v0
	v_exp_f32_e32 v21, v2
	v_sub_f32_e32 v2, v22, v181
	v_add_f32_e32 v0, v18, v0
	v_exp_f32_e32 v22, v2
	v_sub_f32_e32 v2, v23, v181
	v_add_f32_e32 v0, v19, v0
	v_exp_f32_e32 v23, v2
	v_sub_f32_e32 v2, v24, v181
	v_add_f32_e32 v0, v20, v0
	v_exp_f32_e32 v24, v2
	v_sub_f32_e32 v2, v25, v181
	v_add_f32_e32 v0, v21, v0
	v_exp_f32_e32 v25, v2
	v_sub_f32_e32 v2, v26, v181
	v_add_f32_e32 v0, v22, v0
	v_exp_f32_e32 v26, v2
	v_sub_f32_e32 v2, v27, v181
	v_add_f32_e32 v0, v23, v0
	v_exp_f32_e32 v27, v2
	v_sub_f32_e32 v2, v28, v181
	v_add_f32_e32 v0, v24, v0
	v_exp_f32_e32 v28, v2
	v_sub_f32_e32 v2, v29, v181
	v_add_f32_e32 v0, v25, v0
	v_exp_f32_e32 v29, v2
	v_sub_f32_e32 v2, v30, v181
	v_add_f32_e32 v0, v26, v0
	v_exp_f32_e32 v30, v2
	v_sub_f32_e32 v2, v31, v181
	v_add_f32_e32 v0, v27, v0
	v_exp_f32_e32 v31, v2
	v_sub_f32_e32 v2, v32, v181
	v_add_f32_e32 v0, v28, v0
	v_exp_f32_e32 v32, v2
	v_sub_f32_e32 v2, v33, v181
	v_add_f32_e32 v0, v29, v0
	v_exp_f32_e32 v33, v2
	v_sub_f32_e32 v2, v34, v181
	v_add_f32_e32 v0, v30, v0
	v_exp_f32_e32 v34, v2
	v_sub_f32_e32 v2, v35, v181
	v_add_f32_e32 v0, v31, v0
	v_exp_f32_e32 v35, v2
	v_sub_f32_e32 v2, v36, v181
	v_add_f32_e32 v0, v32, v0
	v_exp_f32_e32 v36, v2
	v_sub_f32_e32 v2, v37, v181
	v_add_f32_e32 v0, v33, v0
	v_exp_f32_e32 v37, v2
	v_sub_f32_e32 v2, v38, v181
	v_add_f32_e32 v0, v34, v0
	v_exp_f32_e32 v38, v2
	v_sub_f32_e32 v2, v39, v181
	v_add_f32_e32 v0, v35, v0
	v_exp_f32_e32 v39, v2
	v_sub_f32_e32 v2, v40, v181
	v_add_f32_e32 v0, v36, v0
	v_exp_f32_e32 v40, v2
	v_sub_f32_e32 v2, v41, v181
	v_add_f32_e32 v0, v37, v0
	v_exp_f32_e32 v41, v2
	v_sub_f32_e32 v2, v42, v181
	v_add_f32_e32 v0, v38, v0
	v_exp_f32_e32 v42, v2
	v_sub_f32_e32 v2, v43, v181
	v_add_f32_e32 v0, v39, v0
	v_exp_f32_e32 v43, v2
	v_sub_f32_e32 v2, v44, v181
	v_add_f32_e32 v0, v40, v0
	v_exp_f32_e32 v44, v2
	v_sub_f32_e32 v2, v45, v181
	v_add_f32_e32 v0, v41, v0
	v_exp_f32_e32 v45, v2
	v_sub_f32_e32 v2, v46, v181
	v_add_f32_e32 v0, v42, v0
	v_exp_f32_e32 v46, v2
	v_sub_f32_e32 v2, v47, v181
	v_add_f32_e32 v0, v43, v0
	v_exp_f32_e32 v47, v2
	v_add_f32_e32 v0, v44, v0
	v_add_f32_e32 v0, v45, v0
	v_add_f32_e32 v0, v46, v0
	v_add_f32_e32 v0, v47, v0
	v_add_f32_e32 v180, v180, v0
	v_cvt_pk_bf16_f32 v2, v16, v17
	v_cvt_pk_bf16_f32 v3, v18, v19
	v_cvt_pk_bf16_f32 v4, v20, v21
	v_cvt_pk_bf16_f32 v5, v22, v23
	v_cvt_pk_bf16_f32 v6, v24, v25
	v_cvt_pk_bf16_f32 v7, v26, v27
	v_cvt_pk_bf16_f32 v8, v28, v29
	v_cvt_pk_bf16_f32 v9, v30, v31
	v_cvt_pk_bf16_f32 v10, v32, v33
	v_cvt_pk_bf16_f32 v11, v34, v35
	v_cvt_pk_bf16_f32 v12, v36, v37
	v_cvt_pk_bf16_f32 v13, v38, v39
	v_cvt_pk_bf16_f32 v182, v40, v41
	v_cvt_pk_bf16_f32 v183, v42, v43
	v_cvt_pk_bf16_f32 v184, v44, v45
	v_cvt_pk_bf16_f32 v185, v46, v47
	v_add_u32_e32 v0, s54, v175
	v_add_u32_e32 v14, v0, v176
	s_setprio 1
	ds_read_b128 v[186:189], v14
	ds_read_b128 v[190:193], v14 offset:4096
	ds_read_b128 v[194:197], v14 offset:8192
	ds_read_b128 v[202:205], v14 offset:12288
	v_add_u32_e32 v15, v0, v177
	ds_read_b128 v[206:209], v15
	ds_read_b128 v[210:213], v15 offset:4096
	v_add_u32_e32 v14, v0, v178
	v_add_u32_e32 v0, v0, v179
	s_waitcnt lgkmcnt(5)
	v_mfma_f32_32x32x16_bf16 v[96:111], v[186:189], v[2:5], v[96:111]
	ds_read_b128 v[186:189], v15 offset:8192
	s_waitcnt lgkmcnt(5)
	v_mfma_f32_32x32x16_bf16 v[80:95], v[190:193], v[2:5], v[80:95]
	ds_read_b128 v[190:193], v15 offset:12288
	s_waitcnt lgkmcnt(5)
	v_mfma_f32_32x32x16_bf16 v[64:79], v[194:197], v[2:5], v[64:79]
	ds_read_b128 v[194:197], v14
	s_waitcnt lgkmcnt(5)
	v_mfma_f32_32x32x16_bf16 v[48:63], v[202:205], v[2:5], v[48:63]
	ds_read_b128 v[2:5], v14 offset:4096
	s_waitcnt lgkmcnt(5)
	v_mfma_f32_32x32x16_bf16 v[96:111], v[206:209], v[6:9], v[96:111]
	ds_read_b128 v[202:205], v14 offset:8192
	s_waitcnt lgkmcnt(5)
	v_mfma_f32_32x32x16_bf16 v[80:95], v[210:213], v[6:9], v[80:95]
	ds_read_b128 v[206:209], v14 offset:12288
	s_waitcnt lgkmcnt(5)
	v_mfma_f32_32x32x16_bf16 v[64:79], v[186:189], v[6:9], v[64:79]
	ds_read_b128 v[186:189], v0
	s_waitcnt lgkmcnt(5)
	v_mfma_f32_32x32x16_bf16 v[48:63], v[190:193], v[6:9], v[48:63]
	ds_read_b128 v[6:9], v0 offset:4096
	s_waitcnt lgkmcnt(5)
	v_mfma_f32_32x32x16_bf16 v[96:111], v[194:197], v[10:13], v[96:111]
	ds_read_b128 v[190:193], v0 offset:8192
	s_waitcnt lgkmcnt(5)
	v_mfma_f32_32x32x16_bf16 v[80:95], v[2:5], v[10:13], v[80:95]
	ds_read_b128 v[2:5], v0 offset:12288
	s_waitcnt lgkmcnt(5)
	v_mfma_f32_32x32x16_bf16 v[64:79], v[202:205], v[10:13], v[64:79]
	s_waitcnt lgkmcnt(4)
	v_mfma_f32_32x32x16_bf16 v[48:63], v[206:209], v[10:13], v[48:63]
	s_waitcnt lgkmcnt(3)
	v_mfma_f32_32x32x16_bf16 v[96:111], v[186:189], v[182:185], v[96:111]
	s_waitcnt lgkmcnt(2)
	v_mfma_f32_32x32x16_bf16 v[80:95], v[6:9], v[182:185], v[80:95]
	s_waitcnt lgkmcnt(1)
	v_mfma_f32_32x32x16_bf16 v[64:79], v[190:193], v[182:185], v[64:79]
	s_waitcnt lgkmcnt(0)
	v_mfma_f32_32x32x16_bf16 v[48:63], v[2:5], v[182:185], v[48:63]
	s_setprio 0
; #define LAS __attribute__((address_space(3)))
; template <bool MLA, bool grpB>
; __device__ __forceinline__ void attn_unit_g(LAS unsigned char* lds, const AttnPtrs& P, int b, int h, int qblk) {
;     ...
;     auto qk = [&](int koff) {
;         if (MLA) {
;         } else {
; #pragma unroll
;             for (int blk = 0; blk < 2; ++blk)
; #pragma unroll
;                 for (int g = 0; g < 4; ++g) { const f32x4 c4 = *(const LAS f32x4*)(lds + koff + KTILE + (32 * blk + 16 * hi + 4 * g) * 4);
; #pragma unroll
;                     for (int e = 0; e < 4; ++e) sc[blk][4 * g + e] = c4[e]; }
;         }
;         const LAS unsigned char* ka = lds + koff + karow;
;         bf16x8 a[PFD];
;         auto ld = [&](int i) -> bf16x8 {
;             const int d0 = i >> 1, blk = i & 1, seg = 2 * d0;
;             int so;
;             if (MLA) so = (((seg + hi) & 24) | (((seg + hi) ^ kswz) & 7)) * 16; else so = ((seg + hi) ^ kswz) * 16;
;             return *(const LAS bf16x8*)(ka + blk * 32 * KROW + so);
;         };
; #pragma unroll
;         for (int i = 0; i < PFD; ++i) a[i] = ld(i);
; #pragma unroll
;         for (int i = 0; i < 2 * ND0; ++i) {
;             const f32x16 zc = {0.f, 0.f, 0.f, 0.f, 0.f, 0.f, 0.f, 0.f, 0.f, 0.f, 0.f, 0.f, 0.f, 0.f, 0.f, 0.f};
;             sc[i & 1] = __builtin_amdgcn_mfma_f32_32x32x16_bf16(a[i % PFD], qf[i >> 1], (MLA && i < 2) ? zc : sc[i & 1], 0, 0, 0);
;             if (i + PFD < 2 * ND0) a[i % PFD] = ld(i + PFD);
;         }
;         __builtin_amdgcn_sched_group_barrier(0x100, PFD, 0);
; #pragma unroll
;         for (int i = 0; i < 2 * ND0; ++i) { __builtin_amdgcn_sched_group_barrier(0x008, 1, 0); __builtin_amdgcn_sched_group_barrier(0x100, 1, 0); }
;         __builtin_amdgcn_sched_barrier(0);
.LBB0_1269:
	s_cmpk_eq_i32 s64, 0xff40
	s_cselect_b64 s[8:9], -1, 0
	s_cmp_gt_i32 s48, s97
	s_cselect_b64 s[10:11], -1, 0
	s_or_b64 s[8:9], s[8:9], s[10:11]
	s_and_b64 vcc, exec, s[8:9]
	s_cbranch_vccnz .LBB0_1273
	s_add_i32 s8, s56, 0
	v_add_u32_e32 v0, s8, v161
	s_setprio 1
	ds_read_b128 v[16:19], v0 offset:16384
	ds_read_b128 v[20:23], v0 offset:16400
	ds_read_b128 v[24:27], v0 offset:16416
	ds_read_b128 v[28:31], v0 offset:16432
	ds_read_b128 v[32:35], v0 offset:16512
	ds_read_b128 v[36:39], v0 offset:16528
	ds_read_b128 v[40:43], v0 offset:16544
	ds_read_b128 v[44:47], v0 offset:16560
	v_add_u32_e32 v0, s8, v147
	v_add_u32_e32 v6, v0, v162
	v_add_u32_e32 v7, v0, v163
	v_add_u32_e32 v8, v0, v164
	v_add_u32_e32 v9, v0, v165
	v_add_u32_e32 v10, v0, v166
	v_add_u32_e32 v11, v0, v167
	v_add_u32_e32 v12, v0, v168
	v_add_u32_e32 v0, v0, v169
	ds_read_b128 v[182:185], v6 offset:8192
	ds_read_b128 v[186:189], v7 offset:8192
	ds_read_b128 v[190:193], v8 offset:8192
	ds_read_b128 v[194:197], v9 offset:8192
	ds_read_b128 v[202:205], v10 offset:8192
	ds_read_b128 v[210:213], v11 offset:8192
	s_waitcnt lgkmcnt(5)
	v_mfma_f32_32x32x16_bf16 v[32:47], v[182:185], v[136:139], v[32:47]
	ds_read_b128 v[182:185], v12 offset:8192
	s_waitcnt lgkmcnt(5)
	v_mfma_f32_32x32x16_bf16 v[32:47], v[186:189], v[112:115], v[32:47]
	ds_read_b128 v[186:189], v0 offset:8192
	s_waitcnt lgkmcnt(5)
	v_mfma_f32_32x32x16_bf16 v[32:47], v[190:193], v[116:119], v[32:47]
	ds_read_b128 v[190:193], v6
	s_waitcnt lgkmcnt(5)
	v_mfma_f32_32x32x16_bf16 v[32:47], v[194:197], v[120:123], v[32:47]
	ds_read_b128 v[194:197], v7
	s_waitcnt lgkmcnt(5)
	v_mfma_f32_32x32x16_bf16 v[32:47], v[202:205], v[124:127], v[32:47]
	ds_read_b128 v[202:205], v8
	s_waitcnt lgkmcnt(5)
	v_mfma_f32_32x32x16_bf16 v[32:47], v[210:213], v[128:131], v[32:47]
	ds_read_b128 v[210:213], v9
	s_waitcnt lgkmcnt(5)
	v_mfma_f32_32x32x16_bf16 v[32:47], v[182:185], v[132:135], v[32:47]
	ds_read_b128 v[182:185], v10
	s_waitcnt lgkmcnt(5)
	v_mfma_f32_32x32x16_bf16 v[32:47], v[186:189], v[140:143], v[32:47]
	ds_read_b128 v[186:189], v11
	s_waitcnt lgkmcnt(5)
	v_mfma_f32_32x32x16_bf16 v[16:31], v[190:193], v[136:139], v[16:31]
	ds_read_b128 v[190:193], v12
	s_waitcnt lgkmcnt(5)
	v_mfma_f32_32x32x16_bf16 v[16:31], v[194:197], v[112:115], v[16:31]
	ds_read_b128 v[194:197], v0
	s_waitcnt lgkmcnt(5)
	v_mfma_f32_32x32x16_bf16 v[16:31], v[202:205], v[116:119], v[16:31]
	s_waitcnt lgkmcnt(4)
	v_mfma_f32_32x32x16_bf16 v[16:31], v[210:213], v[120:123], v[16:31]
	s_waitcnt lgkmcnt(3)
	v_mfma_f32_32x32x16_bf16 v[16:31], v[182:185], v[124:127], v[16:31]
	s_waitcnt lgkmcnt(2)
	v_mfma_f32_32x32x16_bf16 v[16:31], v[186:189], v[128:131], v[16:31]
	s_waitcnt lgkmcnt(1)
	v_mfma_f32_32x32x16_bf16 v[16:31], v[190:193], v[132:135], v[16:31]
	s_waitcnt lgkmcnt(0)
	v_mfma_f32_32x32x16_bf16 v[16:31], v[194:197], v[140:143], v[16:31]
	s_setprio 0
	s_mov_b64 s[8:9], -1
	s_and_b64 vcc, exec, s[74:75]
	s_cbranch_vccnz .LBB0_1274

; #define LAS __attribute__((address_space(3)))
; template <bool MLA, bool grpB>
; __device__ __forceinline__ void attn_unit_g(LAS unsigned char* lds, const AttnPtrs& P, int b, int h, int qblk) {
;     ...
;     auto qk = [&](int koff) {
;         if (MLA) {
;         } else {
; #pragma unroll
;             for (int blk = 0; blk < 2; ++blk)
; #pragma unroll
;                 for (int g = 0; g < 4; ++g) { const f32x4 c4 = *(const LAS f32x4*)(lds + koff + KTILE + (32 * blk + 16 * hi + 4 * g) * 4);
; #pragma unroll
;                     for (int e = 0; e < 4; ++e) sc[blk][4 * g + e] = c4[e]; }
;         }
;         const LAS unsigned char* ka = lds + koff + karow;
;         bf16x8 a[PFD];
;         auto ld = [&](int i) -> bf16x8 {
;             const int d0 = i >> 1, blk = i & 1, seg = 2 * d0;
;             int so;
;             if (MLA) so = (((seg + hi) & 24) | (((seg + hi) ^ kswz) & 7)) * 16; else so = ((seg + hi) ^ kswz) * 16;
;             return *(const LAS bf16x8*)(ka + blk * 32 * KROW + so);
;         };
; #pragma unroll
;         for (int i = 0; i < PFD; ++i) a[i] = ld(i);
; #pragma unroll
;         for (int i = 0; i < 2 * ND0; ++i) {
;             const f32x16 zc = {0.f, 0.f, 0.f, 0.f, 0.f, 0.f, 0.f, 0.f, 0.f, 0.f, 0.f, 0.f, 0.f, 0.f, 0.f, 0.f};
;             sc[i & 1] = __builtin_amdgcn_mfma_f32_32x32x16_bf16(a[i % PFD], qf[i >> 1], (MLA && i < 2) ? zc : sc[i & 1], 0, 0, 0);
;             if (i + PFD < 2 * ND0) a[i % PFD] = ld(i + PFD);
;         }
;         __builtin_amdgcn_sched_group_barrier(0x100, PFD, 0);
; #pragma unroll
;         for (int i = 0; i < 2 * ND0; ++i) { __builtin_amdgcn_sched_group_barrier(0x008, 1, 0); __builtin_amdgcn_sched_group_barrier(0x100, 1, 0); }
;         __builtin_amdgcn_sched_barrier(0);
;     };
;     float mref = -1e30f;
;     auto sm = [&](int j) {
;         if (j >= my_last) {
;             if (MLA) { if (j > my_last) {
; #pragma unroll
;                 for (int r = 0; r < 16; ++r) { sc[0][r] = -2e30f; sc[1][r] = -2e30f; } } }
;             else { const int qpos = q0 + r32;
; #pragma unroll
;                 for (int blk = 0; blk < 2; ++blk)
; #pragma unroll
;                     for (int r = 0; r < 16; ++r) { const int key = 64 * j + 32 * blk + 16 * hi + r; if (key > qpos) sc[blk][r] = -2e30f; } }
.LBB0_1313:
	s_add_i32 s8, s51, 0
	v_add_u32_e32 v0, s8, v161
	s_setprio 1
	ds_read_b128 v[96:99], v0 offset:16384
	ds_read_b128 v[100:103], v0 offset:16400
	ds_read_b128 v[104:107], v0 offset:16416
	ds_read_b128 v[108:111], v0 offset:16432
	ds_read_b128 v[80:83], v0 offset:16512
	ds_read_b128 v[84:87], v0 offset:16528
	ds_read_b128 v[88:91], v0 offset:16544
	ds_read_b128 v[92:95], v0 offset:16560
	v_add_u32_e32 v0, s8, v147
	v_add_u32_e32 v6, v0, v162
	v_add_u32_e32 v7, v0, v163
	v_add_u32_e32 v8, v0, v164
	v_add_u32_e32 v9, v0, v165
	v_add_u32_e32 v10, v0, v166
	v_add_u32_e32 v11, v0, v167
	v_add_u32_e32 v12, v0, v168
	v_add_u32_e32 v0, v0, v169
	ds_read_b128 v[182:185], v6 offset:8192
	ds_read_b128 v[186:189], v7 offset:8192
	ds_read_b128 v[190:193], v8 offset:8192
	ds_read_b128 v[194:197], v9 offset:8192
	ds_read_b128 v[202:205], v10 offset:8192
	ds_read_b128 v[210:213], v11 offset:8192
	s_waitcnt lgkmcnt(5)
	v_mfma_f32_32x32x16_bf16 v[80:95], v[182:185], v[136:139], v[80:95]
	ds_read_b128 v[182:185], v12 offset:8192
	s_waitcnt lgkmcnt(5)
	v_mfma_f32_32x32x16_bf16 v[80:95], v[186:189], v[112:115], v[80:95]
	ds_read_b128 v[186:189], v0 offset:8192
	s_waitcnt lgkmcnt(5)
	v_mfma_f32_32x32x16_bf16 v[80:95], v[190:193], v[116:119], v[80:95]
	ds_read_b128 v[190:193], v6
	s_waitcnt lgkmcnt(5)
	v_mfma_f32_32x32x16_bf16 v[80:95], v[194:197], v[120:123], v[80:95]
	ds_read_b128 v[194:197], v7
	s_waitcnt lgkmcnt(5)
	v_mfma_f32_32x32x16_bf16 v[80:95], v[202:205], v[124:127], v[80:95]
	ds_read_b128 v[202:205], v8
	s_waitcnt lgkmcnt(5)
	v_mfma_f32_32x32x16_bf16 v[80:95], v[210:213], v[128:131], v[80:95]
	ds_read_b128 v[210:213], v9
	s_waitcnt lgkmcnt(5)
	v_mfma_f32_32x32x16_bf16 v[80:95], v[182:185], v[132:135], v[80:95]
	ds_read_b128 v[182:185], v10
	s_waitcnt lgkmcnt(5)
	v_mfma_f32_32x32x16_bf16 v[80:95], v[186:189], v[140:143], v[80:95]
	ds_read_b128 v[186:189], v11
	s_waitcnt lgkmcnt(5)
	v_mfma_f32_32x32x16_bf16 v[96:111], v[190:193], v[136:139], v[96:111]
	ds_read_b128 v[190:193], v12
	s_waitcnt lgkmcnt(5)
	v_mfma_f32_32x32x16_bf16 v[96:111], v[194:197], v[112:115], v[96:111]
	ds_read_b128 v[194:197], v0
	s_waitcnt lgkmcnt(5)
	v_mfma_f32_32x32x16_bf16 v[96:111], v[202:205], v[116:119], v[96:111]
	s_waitcnt lgkmcnt(4)
	v_mfma_f32_32x32x16_bf16 v[96:111], v[210:213], v[120:123], v[96:111]
	s_waitcnt lgkmcnt(3)
	v_mfma_f32_32x32x16_bf16 v[96:111], v[182:185], v[124:127], v[96:111]
	s_waitcnt lgkmcnt(2)
	v_mfma_f32_32x32x16_bf16 v[96:111], v[186:189], v[128:131], v[96:111]
	s_waitcnt lgkmcnt(1)
	v_mfma_f32_32x32x16_bf16 v[96:111], v[190:193], v[132:135], v[96:111]
	s_waitcnt lgkmcnt(0)
	v_mfma_f32_32x32x16_bf16 v[96:111], v[194:197], v[140:143], v[96:111]
	s_setprio 0
	s_cmp_lt_u32 s10, s54
	s_cbranch_scc1 .LBB0_1317
	v_add_u32_e32 v0, s64, v146
	v_add_u32_e32 v2, 0xc0, v0
	v_cmp_le_i32_e32 vcc, v2, v173
	v_cmp_lt_i32_e64 s[8:9], v2, v173
	v_add_u32_e32 v2, 0xc2, v0
	v_cmp_le_i32_e64 s[10:11], v2, v173
	v_add_u32_e32 v2, 0xc3, v0
	v_cmp_le_i32_e64 s[12:13], v2, v173
	v_add_u32_e32 v2, 0xc4, v0
	v_cmp_le_i32_e64 s[14:15], v2, v173
	v_add_u32_e32 v2, 0xc5, v0
	v_cmp_le_i32_e64 s[16:17], v2, v173
	v_add_u32_e32 v2, 0xc6, v0
	v_cmp_le_i32_e64 s[18:19], v2, v173
	v_add_u32_e32 v2, 0xc7, v0
	v_cmp_le_i32_e64 s[20:21], v2, v173
	v_add_u32_e32 v2, 0xc8, v0
	v_cmp_le_i32_e64 s[22:23], v2, v173
	v_add_u32_e32 v2, 0xc9, v0
	v_cmp_le_i32_e64 s[24:25], v2, v173
	v_add_u32_e32 v2, 0xca, v0
	v_cmp_le_i32_e64 s[26:27], v2, v173
	v_add_u32_e32 v2, 0xcb, v0
	v_cmp_le_i32_e64 s[28:29], v2, v173
	v_add_u32_e32 v2, 0xcc, v0
	v_cmp_le_i32_e64 s[30:31], v2, v173
	v_add_u32_e32 v2, 0xcd, v0
	v_cmp_le_i32_e64 s[34:35], v2, v173
	v_add_u32_e32 v2, 0xce, v0
	v_cmp_le_i32_e64 s[36:37], v2, v173
	v_add_u32_e32 v2, 0xcf, v0
	v_cmp_le_i32_e64 s[38:39], v2, v173
	v_add_u32_e32 v2, 0xe0, v0
	v_cmp_le_i32_e64 s[42:43], v2, v173
	v_add_u32_e32 v2, 0xe1, v0
	s_nop 0
	v_cndmask_b32_e64 v80, v159, v80, s[42:43]
	v_cmp_le_i32_e64 s[42:43], v2, v173
	v_add_u32_e32 v2, 0xe2, v0
	s_nop 0
	v_cndmask_b32_e64 v81, v159, v81, s[42:43]
	v_cmp_le_i32_e64 s[42:43], v2, v173
	v_add_u32_e32 v2, 0xe3, v0
	s_nop 0
	v_cndmask_b32_e64 v82, v159, v82, s[42:43]
	v_cmp_le_i32_e64 s[42:43], v2, v173
	v_add_u32_e32 v2, 0xe4, v0
	s_nop 0
	v_cndmask_b32_e64 v83, v159, v83, s[42:43]
	v_cmp_le_i32_e64 s[42:43], v2, v173
	v_add_u32_e32 v2, 0xe5, v0
	s_nop 0
	v_cndmask_b32_e64 v84, v159, v84, s[42:43]
	v_cmp_le_i32_e64 s[42:43], v2, v173
	v_add_u32_e32 v2, 0xe6, v0
	s_nop 0
	v_cndmask_b32_e64 v85, v159, v85, s[42:43]
	v_cmp_le_i32_e64 s[42:43], v2, v173
	v_add_u32_e32 v2, 0xe7, v0
	s_nop 0
	v_cndmask_b32_e64 v86, v159, v86, s[42:43]
	v_cmp_le_i32_e64 s[42:43], v2, v173
	v_add_u32_e32 v2, 0xe8, v0
	s_nop 0
	v_cndmask_b32_e64 v87, v159, v87, s[42:43]
	v_cmp_le_i32_e64 s[42:43], v2, v173
	v_add_u32_e32 v2, 0xe9, v0
	s_nop 0
	v_cndmask_b32_e64 v88, v159, v88, s[42:43]
	v_cmp_le_i32_e64 s[42:43], v2, v173
	v_add_u32_e32 v2, 0xea, v0
	s_nop 0
	v_cndmask_b32_e64 v89, v159, v89, s[42:43]
	v_cmp_le_i32_e64 s[42:43], v2, v173
	v_add_u32_e32 v2, 0xeb, v0
	s_nop 0
	v_cndmask_b32_e64 v90, v159, v90, s[42:43]
	v_cmp_le_i32_e64 s[42:43], v2, v173
	v_add_u32_e32 v2, 0xec, v0
	s_nop 0
	v_cndmask_b32_e64 v91, v159, v91, s[42:43]
	v_cmp_le_i32_e64 s[42:43], v2, v173
	v_add_u32_e32 v2, 0xed, v0
	s_nop 0
	v_cndmask_b32_e64 v92, v159, v92, s[42:43]
	v_cmp_le_i32_e64 s[42:43], v2, v173
	v_add_u32_e32 v2, 0xee, v0
	v_add_u32_e32 v0, 0xef, v0
	v_cndmask_b32_e64 v93, v159, v93, s[42:43]
	v_cmp_le_i32_e64 s[42:43], v2, v173
	s_nop 1
	v_cndmask_b32_e64 v94, v159, v94, s[42:43]
	v_cmp_gt_i32_e64 s[42:43], v0, v173
	s_and_saveexec_b64 s[76:77], s[42:43]
	v_mov_b32_e32 v95, s87
	s_or_b64 exec, exec, s[76:77]
	v_cndmask_b32_e64 v97, v159, v97, s[8:9]
	v_cndmask_b32_e32 v96, v159, v96, vcc
	v_cndmask_b32_e64 v98, v159, v98, s[10:11]
	v_cndmask_b32_e64 v99, v159, v99, s[12:13]
	v_cndmask_b32_e64 v100, v159, v100, s[14:15]
	v_cndmask_b32_e64 v101, v159, v101, s[16:17]
	v_cndmask_b32_e64 v102, v159, v102, s[18:19]
	v_cndmask_b32_e64 v103, v159, v103, s[20:21]
	v_cndmask_b32_e64 v104, v159, v104, s[22:23]
	v_cndmask_b32_e64 v105, v159, v105, s[24:25]
	v_cndmask_b32_e64 v106, v159, v106, s[26:27]
	v_cndmask_b32_e64 v107, v159, v107, s[28:29]
	v_cndmask_b32_e64 v108, v159, v108, s[30:31]
	v_cndmask_b32_e64 v109, v159, v109, s[34:35]
	v_cndmask_b32_e64 v110, v159, v110, s[36:37]
	v_cndmask_b32_e64 v111, v159, v111, s[38:39]

; __device__ __forceinline__ unsigned cvt_pk_bf16(float lo, float hi) { unsigned r; asm volatile("v_cvt_pk_bf16_f32 %0, %1, %2" : "=v"(r) : "v"(lo), "v"(hi)); return r; }
; #define LAS __attribute__((address_space(3)))
; template <bool MLA, bool grpB>
; __device__ __forceinline__ void attn_unit_g(LAS unsigned char* lds, const AttnPtrs& P, int b, int h, int qblk) {
;     ...
;         float ps = 0.f;
; #pragma unroll
;         for (int blk = 0; blk < 2; ++blk)
; #pragma unroll
;             for (int r = 0; r < 16; ++r) { const float pv_ = __builtin_amdgcn_exp2f(sc[blk][r] - mref); sc[blk][r] = pv_; ps += pv_; }
;         lrun += ps;
; #pragma unroll
;         for (int blk = 0; blk < 2; ++blk)
; #pragma unroll
;             for (int ks = 0; ks < 2; ++ks) { u32x4 w;
;                 w.x = pg8::cvt_pk_bf16(sc[blk][8 * ks + 0], sc[blk][8 * ks + 1]); w.y = pg8::cvt_pk_bf16(sc[blk][8 * ks + 2], sc[blk][8 * ks + 3]);
;                 w.z = pg8::cvt_pk_bf16(sc[blk][8 * ks + 4], sc[blk][8 * ks + 5]); w.w = pg8::cvt_pk_bf16(sc[blk][8 * ks + 6], sc[blk][8 * ks + 7]);
;                 pb[blk][ks] = __builtin_bit_cast(bf16x8, w); }
;         __builtin_amdgcn_sched_barrier(0);
;     };
;     auto pv = [&](int voff) {
;         const LAS unsigned char* va = lds + varow + voff;
;         bf16x8 a[PFD];
;         auto ld = [&](int i) -> bf16x8 {
;             const int dvb = i & 3, bk = i >> 2, so = ((4 * (bk >> 1) + 2 * hi + (bk & 1)) ^ vswz) * 16;
;             return *(const LAS bf16x8*)(va + 32 * dvb * VROW + so);
;         };
; #pragma unroll
;         for (int i = 0; i < PFD; ++i) a[i] = ld(i);
; #pragma unroll
;         for (int i = 0; i < 16; ++i) {
;             o[i & 3] = __builtin_amdgcn_mfma_f32_32x32x16_bf16(a[i % PFD], pb[i >> 3][(i >> 2) & 1], o[i & 3], 0, 0, 0);
;             if (i + PFD < 16) a[i % PFD] = ld(i + PFD);
;         }
;         __builtin_amdgcn_sched_group_barrier(0x100, PFD, 0);
; #pragma unroll
;         for (int i = 0; i < 16; ++i) { __builtin_amdgcn_sched_group_barrier(0x008, 1, 0); __builtin_amdgcn_sched_group_barrier(0x100, 1, 0); }
;         __builtin_amdgcn_sched_barrier(0);
.LBB0_1319:
	v_sub_f32_e32 v0, v96, v181
	v_exp_f32_e32 v0, v0
	v_sub_f32_e32 v2, v97, v181
	v_exp_f32_e32 v2, v2
	v_sub_f32_e32 v3, v98, v181
	v_exp_f32_e32 v3, v3
	v_sub_f32_e32 v4, v99, v181
	v_exp_f32_e32 v4, v4
	v_sub_f32_e32 v6, v100, v181
	v_add_f32_e32 v5, 0, v0
	v_exp_f32_e32 v6, v6
	v_sub_f32_e32 v7, v101, v181
	v_add_f32_e32 v5, v2, v5
	v_exp_f32_e32 v7, v7
	v_sub_f32_e32 v8, v102, v181
	v_add_f32_e32 v5, v3, v5
	v_exp_f32_e32 v8, v8
	v_sub_f32_e32 v9, v103, v181
	v_add_f32_e32 v5, v4, v5
	v_exp_f32_e32 v9, v9
	v_sub_f32_e32 v10, v104, v181
	v_add_f32_e32 v5, v6, v5
	v_exp_f32_e32 v10, v10
	v_sub_f32_e32 v11, v105, v181
	v_add_f32_e32 v5, v7, v5
	v_exp_f32_e32 v11, v11
	v_sub_f32_e32 v12, v106, v181
	v_add_f32_e32 v5, v8, v5
	v_exp_f32_e32 v12, v12
	v_sub_f32_e32 v13, v107, v181
	v_add_f32_e32 v5, v9, v5
	v_exp_f32_e32 v13, v13
	v_sub_f32_e32 v14, v108, v181
	v_add_f32_e32 v5, v10, v5
	v_exp_f32_e32 v14, v14
	v_sub_f32_e32 v15, v109, v181
	v_add_f32_e32 v5, v11, v5
	v_exp_f32_e32 v15, v15
	v_sub_f32_e32 v96, v110, v181
	v_add_f32_e32 v5, v12, v5
	v_exp_f32_e32 v96, v96
	v_sub_f32_e32 v97, v111, v181
	v_add_f32_e32 v5, v13, v5
	v_exp_f32_e32 v97, v97
	v_sub_f32_e32 v80, v80, v181
	v_add_f32_e32 v5, v14, v5
	v_exp_f32_e32 v80, v80
	v_sub_f32_e32 v81, v81, v181
	v_add_f32_e32 v5, v15, v5
	v_exp_f32_e32 v81, v81
	v_sub_f32_e32 v82, v82, v181
	v_add_f32_e32 v5, v96, v5
	v_exp_f32_e32 v82, v82
	v_sub_f32_e32 v83, v83, v181
	v_add_f32_e32 v5, v97, v5
	v_exp_f32_e32 v83, v83
	v_sub_f32_e32 v84, v84, v181
	v_add_f32_e32 v5, v80, v5
	v_exp_f32_e32 v84, v84
	v_sub_f32_e32 v85, v85, v181
	v_add_f32_e32 v5, v81, v5
	v_exp_f32_e32 v85, v85
	v_sub_f32_e32 v86, v86, v181
	v_add_f32_e32 v5, v82, v5
	v_exp_f32_e32 v86, v86
	v_sub_f32_e32 v87, v87, v181
	v_add_f32_e32 v5, v83, v5
	v_exp_f32_e32 v87, v87
	v_sub_f32_e32 v88, v88, v181
	v_add_f32_e32 v5, v84, v5
	v_exp_f32_e32 v88, v88
	v_sub_f32_e32 v89, v89, v181
	v_add_f32_e32 v5, v85, v5
	v_exp_f32_e32 v89, v89
	v_sub_f32_e32 v90, v90, v181
	v_add_f32_e32 v5, v86, v5
	v_exp_f32_e32 v90, v90
	v_sub_f32_e32 v91, v91, v181
	v_add_f32_e32 v5, v87, v5
	v_exp_f32_e32 v91, v91
	v_sub_f32_e32 v92, v92, v181
	v_add_f32_e32 v5, v88, v5
	v_exp_f32_e32 v92, v92
	v_sub_f32_e32 v93, v93, v181
	v_add_f32_e32 v5, v89, v5
	v_exp_f32_e32 v93, v93
	v_sub_f32_e32 v94, v94, v181
	v_add_f32_e32 v5, v90, v5
	v_exp_f32_e32 v94, v94
	v_sub_f32_e32 v95, v95, v181
	v_add_f32_e32 v5, v91, v5
	v_exp_f32_e32 v95, v95
	v_add_f32_e32 v5, v92, v5
	v_add_f32_e32 v5, v93, v5
	v_add_f32_e32 v5, v94, v5
	v_add_f32_e32 v5, v95, v5
	v_add_f32_e32 v180, v180, v5
	v_cvt_pk_bf16_f32 v2, v0, v2
	v_cvt_pk_bf16_f32 v3, v3, v4
	v_cvt_pk_bf16_f32 v4, v6, v7
	v_cvt_pk_bf16_f32 v5, v8, v9
	v_cvt_pk_bf16_f32 v6, v10, v11
	v_cvt_pk_bf16_f32 v7, v12, v13
	v_cvt_pk_bf16_f32 v8, v14, v15
	v_cvt_pk_bf16_f32 v9, v96, v97
	v_cvt_pk_bf16_f32 v10, v80, v81
	v_cvt_pk_bf16_f32 v11, v82, v83
	v_cvt_pk_bf16_f32 v12, v84, v85
	v_cvt_pk_bf16_f32 v13, v86, v87
	v_cvt_pk_bf16_f32 v80, v88, v89
	v_cvt_pk_bf16_f32 v81, v90, v91
	v_cvt_pk_bf16_f32 v82, v92, v93
	v_cvt_pk_bf16_f32 v83, v94, v95
	v_add_u32_e32 v0, s41, v175
	v_add_u32_e32 v14, v0, v176
	s_setprio 1
	ds_read_b128 v[84:87], v14
	ds_read_b128 v[88:91], v14 offset:4096
	ds_read_b128 v[92:95], v14 offset:8192
	ds_read_b128 v[96:99], v14 offset:12288
	v_add_u32_e32 v15, v0, v177
	ds_read_b128 v[100:103], v15
	ds_read_b128 v[104:107], v15 offset:4096
	v_add_u32_e32 v14, v0, v178
	v_add_u32_e32 v0, v0, v179
	s_waitcnt lgkmcnt(5)
	v_mfma_f32_32x32x16_bf16 v[64:79], v[84:87], v[2:5], v[64:79]
	ds_read_b128 v[84:87], v15 offset:8192
	s_waitcnt lgkmcnt(5)
	v_mfma_f32_32x32x16_bf16 v[48:63], v[88:91], v[2:5], v[48:63]
	ds_read_b128 v[88:91], v15 offset:12288
	s_waitcnt lgkmcnt(5)
	v_mfma_f32_32x32x16_bf16 v[32:47], v[92:95], v[2:5], v[32:47]
	ds_read_b128 v[92:95], v14
	s_waitcnt lgkmcnt(5)
	v_mfma_f32_32x32x16_bf16 v[16:31], v[96:99], v[2:5], v[16:31]
	ds_read_b128 v[2:5], v14 offset:4096
	s_waitcnt lgkmcnt(5)
	v_mfma_f32_32x32x16_bf16 v[64:79], v[100:103], v[6:9], v[64:79]
	ds_read_b128 v[96:99], v14 offset:8192
	s_waitcnt lgkmcnt(5)
	v_mfma_f32_32x32x16_bf16 v[48:63], v[104:107], v[6:9], v[48:63]
	ds_read_b128 v[100:103], v14 offset:12288
	s_waitcnt lgkmcnt(5)
	v_mfma_f32_32x32x16_bf16 v[32:47], v[84:87], v[6:9], v[32:47]
	ds_read_b128 v[84:87], v0
	s_waitcnt lgkmcnt(5)
	v_mfma_f32_32x32x16_bf16 v[16:31], v[88:91], v[6:9], v[16:31]
	ds_read_b128 v[6:9], v0 offset:4096
	s_waitcnt lgkmcnt(5)
	v_mfma_f32_32x32x16_bf16 v[64:79], v[92:95], v[10:13], v[64:79]
	ds_read_b128 v[88:91], v0 offset:8192
	s_waitcnt lgkmcnt(5)
	v_mfma_f32_32x32x16_bf16 v[48:63], v[2:5], v[10:13], v[48:63]
	ds_read_b128 v[2:5], v0 offset:12288
	s_waitcnt lgkmcnt(5)
	v_mfma_f32_32x32x16_bf16 v[32:47], v[96:99], v[10:13], v[32:47]
	s_waitcnt lgkmcnt(4)
	v_mfma_f32_32x32x16_bf16 v[16:31], v[100:103], v[10:13], v[16:31]
	s_waitcnt lgkmcnt(3)
	v_mfma_f32_32x32x16_bf16 v[64:79], v[84:87], v[80:83], v[64:79]
	s_waitcnt lgkmcnt(2)
	v_mfma_f32_32x32x16_bf16 v[48:63], v[6:9], v[80:83], v[48:63]
	s_waitcnt lgkmcnt(1)
	v_mfma_f32_32x32x16_bf16 v[32:47], v[88:91], v[80:83], v[32:47]
	s_waitcnt lgkmcnt(0)
	v_mfma_f32_32x32x16_bf16 v[16:31], v[2:5], v[80:83], v[16:31]
	s_setprio 0
	s_mov_b64 s[8:9], -1
	s_and_b64 vcc, exec, s[74:75]
	s_cbranch_vccnz .LBB0_1325
